# nt cache policy on layer-2 decode streaming loads of the f32 paged cache and fp8 copy stores
# baseline (speedup 1.0000x reference)
.LBB0_2268:
	s_lshl_b32 s17, s14, 5
	s_lshl_b32 s15, s16, 6
	s_and_b32 s17, s17, 32
	s_or_b32 s15, s15, s17
	s_lshl_b32 s17, s1, 2
	s_add_i32 s20, s15, s17
	s_lshl_b32 s2, s1, 14
	s_ashr_i32 s21, s20, 31
	s_add_i32 s10, s2, 0
	s_ashr_i32 s2, s1, 31
	s_lshl_b64 s[20:21], s[20:21], 2
	s_waitcnt lgkmcnt(0)
	s_add_u32 s18, s18, s20
	s_addc_u32 s19, s19, s21
	global_load_dwordx4 v[4:7], v1, s[18:19]
	v_mov_b32_e32 v3, v1
	s_barrier
	v_lshlrev_b32_e32 v0, 3, v36
	v_lshlrev_b32_e32 v38, 2, v36
	v_and_b32_e32 v36, 0x1f0, v0
	v_add_u32_e32 v41, s10, v36
	v_xad_u32 v42, v36, 32, s10
	v_xad_u32 v43, v36, 64, s10
	v_lshrrev_b32_e32 v37, 2, v155
	v_and_b32_e32 v40, 8, v0
	v_lshl_add_u32 v46, v155, 9, s10
	v_xor_b32_e32 v163, 64, v38
	v_xor_b32_e32 v164, 0x80, v38
	v_add_u32_e32 v182, v41, v40
	v_add_u32_e32 v183, v42, v40
	v_add_u32_e32 v184, v43, v40
	s_mov_b32 s15, 4
	s_mov_b32 s17, 0
	v_mov_b32_e32 v165, 0
	v_mov_b32_e32 v154, 0xf149f2ca
	s_movk_i32 s38, 0x2000
	s_waitcnt vmcnt(0)
	v_readfirstlane_b32 s24, v5
	v_readfirstlane_b32 s20, v4
	s_ashr_i32 s21, s20, 31
	s_ashr_i32 s25, s24, 31
	s_lshl_b64 s[22:23], s[24:25], 17
	s_lshl_b64 s[18:19], s[20:21], 17
	s_add_u32 s18, s4, s18
	s_addc_u32 s19, s5, s19
	v_lshl_add_u64 v[10:11], s[18:19], 0, v[2:3]
	v_add_co_u32_e32 v10, vcc, s96, v10
	v_readfirstlane_b32 s34, v7
	s_nop 0
	v_addc_co_u32_e32 v11, vcc, 0, v11, vcc
	v_readfirstlane_b32 s28, v6
	global_load_dwordx4 v[22:25], v2, s[18:19] nt
	global_load_dwordx4 v[14:17], v2, s[18:19] offset:1024 nt
	global_load_dwordx4 v[6:9], v2, s[18:19] offset:2048 nt
	s_nop 0
	global_load_dwordx4 v[2:5], v2, s[18:19] offset:3072 nt
	s_nop 0
	global_load_dwordx4 v[30:33], v[10:11], off nt
	global_load_dwordx4 v[26:29], v[10:11], off offset:1024 nt
	global_load_dwordx4 v[18:21], v[10:11], off offset:2048 nt
	s_nop 0
	global_load_dwordx4 v[10:13], v[10:11], off offset:3072 nt
	s_lshl_b64 s[20:21], s[20:21], 15
	s_add_u32 s20, s8, s20
	s_addc_u32 s21, s9, s21
	s_add_u32 s22, s4, s22
	s_addc_u32 s23, s5, s23
	s_lshl_b64 s[24:25], s[24:25], 15
	s_add_u32 s24, s8, s24
	s_addc_u32 s25, s9, s25
	s_ashr_i32 s29, s28, 31
	s_ashr_i32 s35, s34, 31
	s_lshl_b64 s[30:31], s[34:35], 17
	s_lshl_b64 s[26:27], s[28:29], 17
	s_add_u32 s26, s4, s26
	s_addc_u32 s27, s5, s27
	s_lshl_b64 s[28:29], s[28:29], 15
	s_add_u32 s28, s8, s28
	s_addc_u32 s29, s9, s29
	s_add_u32 s30, s4, s30
	s_addc_u32 s31, s5, s31
	s_lshl_b64 s[4:5], s[34:35], 15
	s_add_u32 s34, s8, s4
	s_movk_i32 s4, 0x60
	v_bitop3_b32 v36, v0, s4, v161 bitop3:0x6c
	s_movk_i32 s4, 0x80
	v_add_u32_e32 v44, s10, v36
	v_bitop3_b32 v36, v0, s4, v161 bitop3:0x6c
	s_movk_i32 s4, 0xa0
	v_add_u32_e32 v45, s10, v36
	v_bitop3_b32 v36, v0, s4, v161 bitop3:0x6c
	s_movk_i32 s4, 0xc0
	v_add_u32_e32 v47, s10, v36
	v_bitop3_b32 v36, v0, s4, v161 bitop3:0x6c
	s_movk_i32 s4, 0xe0
	v_add_u32_e32 v48, s10, v36
	v_bitop3_b32 v36, v0, s4, v161 bitop3:0x6c
	v_add_u32_e32 v49, s10, v36
	v_lshlrev_b32_e32 v36, 1, v155
	v_and_b32_e32 v50, 14, v36
	v_bitop3_b32 v36, v36, v35, 14 bitop3:0x6c
	v_lshlrev_b32_e32 v51, 4, v36
	v_bitop3_b32 v36, v35, v50, 4 bitop3:0x36
	v_lshlrev_b32_e32 v52, 4, v36
	v_bitop3_b32 v36, v35, v50, 8 bitop3:0x36
	v_lshlrev_b32_e32 v53, 4, v36
	v_bitop3_b32 v36, v35, v50, 12 bitop3:0x36
	v_lshlrev_b32_e32 v54, 4, v36
	v_bitop3_b32 v36, v35, v50, 16 bitop3:0x36
	v_lshlrev_b32_e32 v55, 4, v36
	v_bitop3_b32 v36, v35, v50, 20 bitop3:0x36
	v_lshlrev_b32_e32 v56, 4, v36
	v_bitop3_b32 v36, v35, v50, 24 bitop3:0x36
	v_lshlrev_b32_e32 v57, 4, v36
	v_bitop3_b32 v36, v35, v50, 28 bitop3:0x36
	v_lshlrev_b32_e32 v50, 4, v36
	v_lshl_or_b32 v35, v35, 2, v37
	v_bfe_u32 v36, v34, 1, 1
	v_lshlrev_b32_e32 v34, 3, v34
	v_and_b32_e32 v58, 8, v34
	v_lshlrev_b32_e32 v34, 1, v35
	v_and_b32_e32 v37, 14, v34
	v_or_b32_e32 v37, v37, v36
	v_lshl_add_u32 v35, v35, 9, s10
	v_lshl_add_u32 v59, v37, 4, v35
	v_or_b32_e32 v37, 2, v36
	v_bitop3_b32 v37, v34, v37, 14 bitop3:0x6c
	v_lshl_add_u32 v60, v37, 4, v35
	v_or_b32_e32 v37, 4, v36
	v_bitop3_b32 v37, v34, v37, 14 bitop3:0x6c
	v_lshl_add_u32 v61, v37, 4, v35
	v_or_b32_e32 v37, 6, v36
	v_bitop3_b32 v37, v34, v37, 14 bitop3:0x6c
	v_lshl_add_u32 v62, v37, 4, v35
	v_or_b32_e32 v37, 8, v36
	v_bitop3_b32 v37, v34, v37, 14 bitop3:0x6c
	v_lshl_add_u32 v63, v37, 4, v35
	v_or_b32_e32 v37, 10, v36
	v_bitop3_b32 v37, v34, v37, 14 bitop3:0x6c
	v_lshl_add_u32 v64, v37, 4, v35
	v_or_b32_e32 v37, 12, v36
	v_bitop3_b32 v37, v34, v37, 14 bitop3:0x6c
	v_lshl_add_u32 v65, v37, 4, v35
	v_bitop3_b32 v37, v34, v36, 14 bitop3:0x4e
	v_lshl_add_u32 v66, v37, 4, v35
	v_or_b32_e32 v37, v34, v36
	v_lshl_or_b32 v37, v37, 4, v162
	v_add_u32_e32 v67, v35, v37
	v_or_b32_e32 v37, 18, v36
	v_bitop3_b32 v37, v34, v37, 14 bitop3:0x6c
	v_lshl_add_u32 v68, v37, 4, v35
	v_or_b32_e32 v37, 20, v36
	v_bitop3_b32 v37, v34, v37, 14 bitop3:0x6c
	v_lshl_add_u32 v69, v37, 4, v35
	v_or_b32_e32 v37, 22, v36
	s_addc_u32 s35, s9, s5
	v_bitop3_b32 v37, v34, v37, 14 bitop3:0x6c
	v_lshl_add_u32 v70, v37, 4, v35
	v_or_b32_e32 v37, 24, v36
	s_add_u32 s1, s12, s1
	v_bitop3_b32 v37, v34, v37, 14 bitop3:0x6c
	s_addc_u32 s2, s13, s2
	v_lshl_add_u32 v71, v37, 4, v35
	v_or_b32_e32 v37, 26, v36
	s_mul_i32 s2, s2, 0x28000
	s_mul_hi_u32 s4, s1, 0x28000
	v_bitop3_b32 v37, v34, v37, 14 bitop3:0x6c
	s_add_i32 s2, s4, s2
	s_mul_i32 s1, s1, 0x28000
	v_lshl_add_u32 v72, v37, 4, v35
	v_or_b32_e32 v37, 28, v36
	v_or_b32_e32 v36, 30, v36
	s_add_u32 s4, s75, s1
	v_bitop3_b32 v37, v34, v37, 14 bitop3:0x6c
	v_bitop3_b32 v34, v34, v36, 14 bitop3:0x6c
	s_addc_u32 s5, s76, s2
	v_lshl_add_u32 v73, v37, 4, v35
	v_lshl_add_u32 v74, v34, 4, v35
	v_lshl_add_u64 v[152:153], s[4:5], 0, v[0:1]
	v_mov_b32_e32 v36, v1
	v_mov_b32_e32 v37, v1
	v_lshlrev_b32_e32 v0, 2, v38
	v_add_u32_e32 v38, 0, v39
	v_mov_b32_e32 v34, v1
	v_mov_b32_e32 v35, v1
	v_add_u32_e32 v166, v59, v58
	v_add_u32_e32 v167, v60, v58
	v_add_u32_e32 v168, v61, v58
	v_add_u32_e32 v169, v62, v58
	v_add_u32_e32 v170, v63, v58
	v_add_u32_e32 v171, v64, v58
	v_add_u32_e32 v172, v65, v58
	v_add_u32_e32 v173, v66, v58
	v_add_u32_e32 v174, v67, v58
	v_add_u32_e32 v175, v68, v58
	v_add_u32_e32 v176, v69, v58
	v_add_u32_e32 v177, v70, v58
	v_add_u32_e32 v178, v71, v58
	v_add_u32_e32 v179, v72, v58
	v_add_u32_e32 v180, v73, v58
	v_add_u32_e32 v181, v74, v58
	v_add_u32_e32 v185, v44, v40
	v_add_u32_e32 v186, v45, v40
	v_add_u32_e32 v187, v47, v40
	v_add_u32_e32 v188, v48, v40
	v_add_u32_e32 v189, v49, v40
	v_add_u32_e32 v190, v46, v51
	v_add_u32_e32 v191, 0x21000, v38
	v_add_u32_e32 v192, v46, v52
	v_add_u32_e32 v193, v46, v53
	v_add_u32_e32 v194, v46, v54
	v_add_u32_e32 v195, v46, v55
	v_add_u32_e32 v196, v46, v56
	v_add_u32_e32 v197, v46, v57
	v_add_u32_e32 v198, v46, v50
	v_mov_b64_e32 v[96:97], v[36:37]
	v_mov_b64_e32 v[92:93], v[36:37]
	v_mov_b64_e32 v[88:89], v[36:37]
	v_mov_b64_e32 v[84:85], v[36:37]
	v_mov_b64_e32 v[80:81], v[36:37]
	v_mov_b64_e32 v[76:77], v[36:37]
	v_mov_b64_e32 v[72:73], v[36:37]
	v_mov_b64_e32 v[68:69], v[36:37]
	v_mov_b64_e32 v[64:65], v[36:37]
	v_mov_b64_e32 v[60:61], v[36:37]
	v_mov_b64_e32 v[56:57], v[36:37]
	v_mov_b64_e32 v[52:53], v[36:37]
	v_mov_b64_e32 v[48:49], v[36:37]
	v_mov_b64_e32 v[44:45], v[36:37]
	v_mov_b64_e32 v[40:41], v[36:37]
	v_mov_b64_e32 v[94:95], v[34:35]
	v_mov_b64_e32 v[90:91], v[34:35]
	v_mov_b64_e32 v[86:87], v[34:35]
	v_mov_b64_e32 v[82:83], v[34:35]
	v_mov_b64_e32 v[78:79], v[34:35]
	v_mov_b64_e32 v[74:75], v[34:35]
	v_mov_b64_e32 v[70:71], v[34:35]
	v_mov_b64_e32 v[66:67], v[34:35]
	v_mov_b64_e32 v[62:63], v[34:35]
	v_mov_b64_e32 v[58:59], v[34:35]
	v_mov_b64_e32 v[54:55], v[34:35]
	v_mov_b64_e32 v[50:51], v[34:35]
	v_mov_b64_e32 v[46:47], v[34:35]
	v_mov_b64_e32 v[42:43], v[34:35]
	v_mov_b64_e32 v[38:39], v[34:35]
	s_branch .LBB0_2270

.LBB0_2279:
	s_and_b32 s2, s17, 0x60
	s_lshl_b32 s8, s2, 10
	s_add_u32 s8, s36, s8
	s_addc_u32 s9, s37, 0
	v_lshl_add_u64 v[98:99], s[8:9], 0, v[0:1]
	v_add_co_u32_e32 v102, vcc, 0x2000, v98
	v_lshl_add_u64 v[100:101], v[98:99], 0, s[64:65]
	s_nop 0
	v_addc_co_u32_e32 v103, vcc, 0, v99, vcc
	v_add_co_u32_e32 v98, vcc, 0x3000, v98
	global_load_dwordx4 v[138:141], v[100:101], off offset:1024 nt
	global_load_dwordx4 v[134:137], v[100:101], off offset:2048 nt
	global_load_dwordx4 v[142:145], v[102:103], off nt
	global_load_dwordx4 v[130:133], v[100:101], off offset:3072 nt
	v_addc_co_u32_e32 v99, vcc, 0, v99, vcc
	global_load_dwordx4 v[126:129], v[98:99], off nt
	global_load_dwordx4 v[122:125], v[98:99], off offset:1024 nt
	global_load_dwordx4 v[118:121], v[98:99], off offset:2048 nt
	global_load_dwordx4 v[114:117], v[98:99], off offset:3072 nt
	v_cndmask_b32_e64 v98, 0, 1, s[4:5]
	v_cmp_ne_u32_e64 s[8:9], 1, v98
	s_andn2_b64 vcc, exec, s[4:5]
	s_mov_b64 s[36:37], s[20:21]
	s_cbranch_vccnz .LBB0_2288
	s_cmp_lt_i32 s1, 2
	s_cbranch_scc1 .LBB0_2284
	s_cmp_eq_u32 s1, 2
	s_mov_b64 s[4:5], -1
	s_cbranch_scc0 .LBB0_2283
	s_mov_b64 s[4:5], 0

.LBB0_2288:
	v_or_b32_e32 v98, s2, v155
	v_lshlrev_b32_e32 v98, 8, v98
	v_mov_b32_e32 v99, v1
	v_lshl_add_u64 v[98:99], s[36:37], 0, v[98:99]
	v_lshl_add_u64 v[98:99], v[150:151], 2, v[98:99]
	global_load_dwordx4 v[110:113], v[98:99], off offset:16 nt
	global_load_dwordx4 v[106:109], v[98:99], off nt
	global_load_dwordx4 v[102:105], v[98:99], off offset:144 nt
	s_nop 0
	global_load_dwordx4 v[98:101], v[98:99], off offset:128 nt
	s_waitcnt vmcnt(19)
	v_cvt_pk_bf16_f32 v22, v22, v23
	v_cvt_pk_bf16_f32 v23, v24, v25
	ds_write_b64 v182, v[22:23]
	s_waitcnt vmcnt(18)
	v_cvt_pk_bf16_f32 v14, v14, v15
	v_cvt_pk_bf16_f32 v15, v16, v17
	ds_write_b64 v183, v[14:15] offset:512
	s_waitcnt vmcnt(17)
	v_cvt_pk_bf16_f32 v6, v6, v7
	v_cvt_pk_bf16_f32 v7, v8, v9
	ds_write_b64 v184, v[6:7] offset:1024
	s_waitcnt vmcnt(16)
	v_cvt_pk_bf16_f32 v2, v2, v3
	v_cvt_pk_bf16_f32 v3, v4, v5
	ds_write_b64 v185, v[2:3] offset:1536
	s_waitcnt vmcnt(15)
	v_cvt_pk_bf16_f32 v2, v30, v31
	v_cvt_pk_bf16_f32 v3, v32, v33
	ds_write_b64 v186, v[2:3] offset:2048
	s_waitcnt vmcnt(14)
	v_cvt_pk_bf16_f32 v2, v26, v27
	v_cvt_pk_bf16_f32 v3, v28, v29
	ds_write_b64 v187, v[2:3] offset:2560
	s_waitcnt vmcnt(13)
	v_cvt_pk_bf16_f32 v2, v18, v19
	v_cvt_pk_bf16_f32 v3, v20, v21
	ds_write_b64 v188, v[2:3] offset:3072
	s_waitcnt vmcnt(12)
	v_cvt_pk_bf16_f32 v2, v10, v11
	v_cvt_pk_bf16_f32 v3, v12, v13
	ds_write_b64 v189, v[2:3] offset:3584
	s_and_b64 vcc, exec, s[8:9]
	s_mov_b64 s[4:5], s[18:19]
	s_cbranch_vccnz .LBB0_2297
	s_cmp_lt_i32 s1, 2
	s_cbranch_scc1 .LBB0_2293
	s_cmp_eq_u32 s1, 2
	s_mov_b64 s[36:37], -1
	s_cbranch_scc0 .LBB0_2292
	s_mov_b64 s[36:37], 0

.LBB0_2297:
	s_add_i32 s10, s38, 0xffffe000
	s_and_b32 s10, s10, 0x6000
	s_lshl_b32 s10, s10, 2
	s_add_u32 s4, s4, s10
	s_addc_u32 s5, s5, 0
	v_lshl_add_u64 v[2:3], s[4:5], 0, v[0:1]
	s_mov_b64 s[4:5], 0x4000
	v_lshl_add_u64 v[4:5], v[2:3], 0, s[4:5]
	s_movk_i32 s4, 0x5000
	v_add_co_u32_e32 v10, vcc, s4, v2
	s_nop 1
	v_addc_co_u32_e32 v11, vcc, 0, v3, vcc
	global_load_dwordx4 v[14:17], v[4:5], off offset:1024 nt
	global_load_dwordx4 v[6:9], v[4:5], off offset:2048 nt
	global_load_dwordx4 v[22:25], v[10:11], off offset:-4096 nt
	s_nop 0
	global_load_dwordx4 v[2:5], v[4:5], off offset:3072 nt
	s_nop 0
	global_load_dwordx4 v[30:33], v[10:11], off nt
	global_load_dwordx4 v[26:29], v[10:11], off offset:1024 nt
	global_load_dwordx4 v[18:21], v[10:11], off offset:2048 nt
	s_nop 0
	global_load_dwordx4 v[10:13], v[10:11], off offset:3072 nt
	s_waitcnt vmcnt(17)
	v_cvt_pk_bf16_f32 v142, v142, v143
	v_cvt_pk_bf16_f32 v143, v144, v145
	ds_write_b64 v182, v[142:143] offset:4096
	v_cvt_pk_bf16_f32 v138, v138, v139
	v_cvt_pk_bf16_f32 v139, v140, v141
	ds_write_b64 v183, v[138:139] offset:4608
	v_cvt_pk_bf16_f32 v134, v134, v135
	v_cvt_pk_bf16_f32 v135, v136, v137
	ds_write_b64 v184, v[134:135] offset:5120
	s_waitcnt vmcnt(16)
	v_cvt_pk_bf16_f32 v130, v130, v131
	v_cvt_pk_bf16_f32 v131, v132, v133
	ds_write_b64 v185, v[130:131] offset:5632
	s_waitcnt vmcnt(15)
	v_cvt_pk_bf16_f32 v126, v126, v127
	v_cvt_pk_bf16_f32 v127, v128, v129
	ds_write_b64 v186, v[126:127] offset:6144
	s_waitcnt vmcnt(14)
	v_cvt_pk_bf16_f32 v122, v122, v123
	v_cvt_pk_bf16_f32 v123, v124, v125
	ds_write_b64 v187, v[122:123] offset:6656
	s_waitcnt vmcnt(13)
	v_cvt_pk_bf16_f32 v118, v118, v119
	v_cvt_pk_bf16_f32 v119, v120, v121
	ds_write_b64 v188, v[118:119] offset:7168
	s_waitcnt vmcnt(12)
	v_cvt_pk_bf16_f32 v114, v114, v115
	v_cvt_pk_bf16_f32 v115, v116, v117
	ds_write_b64 v189, v[114:115] offset:7680
	ds_read_b128 v[114:117], v190
	v_mov_b32_e32 v119, v1
	s_waitcnt lgkmcnt(0)
	v_lshlrev_b32_e32 v121, 16, v116
	v_and_b32_e32 v122, 0xffff0000, v116
	v_cvt_pk_fp8_f32 v119, v121, v122
	v_lshlrev_b32_e32 v118, 16, v117
	v_and_b32_e32 v120, 0xffff0000, v117
	v_lshlrev_b32_e32 v122, 16, v114
	v_cvt_pk_fp8_f32 v119, v118, v120 op_sel:[0,0,1]
	v_and_b32_e32 v123, 0xffff0000, v114
	v_mov_b32_e32 v118, v1
	v_cvt_pk_fp8_f32 v118, v122, v123
	v_lshlrev_b32_e32 v120, 16, v115
	v_and_b32_e32 v121, 0xffff0000, v115
	v_mov_b32_e32 v123, v1
	v_cvt_pk_fp8_f32 v118, v120, v121 op_sel:[0,0,1]
	global_store_dwordx2 v[152:153], v[118:119], off nt
	ds_read_b128 v[118:121], v191
	s_waitcnt lgkmcnt(0)
	v_mfma_f32_16x16x32_bf16 v[114:117], v[114:117], v[118:121], 0
	ds_read_b128 v[118:121], v192
	s_waitcnt lgkmcnt(0)
	v_lshlrev_b32_e32 v125, 16, v120
	v_and_b32_e32 v126, 0xffff0000, v120
	v_cvt_pk_fp8_f32 v123, v125, v126
	v_lshlrev_b32_e32 v122, 16, v121
	v_and_b32_e32 v124, 0xffff0000, v121
	v_lshlrev_b32_e32 v126, 16, v118
	v_cvt_pk_fp8_f32 v123, v122, v124 op_sel:[0,0,1]
	v_and_b32_e32 v127, 0xffff0000, v118
	v_mov_b32_e32 v122, v1
	v_cvt_pk_fp8_f32 v122, v126, v127
	v_lshlrev_b32_e32 v124, 16, v119
	v_and_b32_e32 v125, 0xffff0000, v119
	v_cvt_pk_fp8_f32 v122, v124, v125 op_sel:[0,0,1]
	global_store_dwordx2 v[152:153], v[122:123], off offset:512 nt
	ds_read_b128 v[122:125], v191 offset:1024
	s_waitcnt lgkmcnt(0)
	v_mfma_f32_16x16x32_bf16 v[114:117], v[118:121], v[122:125], v[114:117]
	ds_read_b128 v[118:121], v193
	v_mov_b32_e32 v123, v1
	s_waitcnt lgkmcnt(0)
	v_lshlrev_b32_e32 v125, 16, v120
	v_and_b32_e32 v126, 0xffff0000, v120
	v_cvt_pk_fp8_f32 v123, v125, v126
	v_lshlrev_b32_e32 v122, 16, v121
	v_and_b32_e32 v124, 0xffff0000, v121
	v_lshlrev_b32_e32 v126, 16, v118
	v_cvt_pk_fp8_f32 v123, v122, v124 op_sel:[0,0,1]
	v_and_b32_e32 v127, 0xffff0000, v118
	v_mov_b32_e32 v122, v1
	v_cvt_pk_fp8_f32 v122, v126, v127
	v_lshlrev_b32_e32 v124, 16, v119
	v_and_b32_e32 v125, 0xffff0000, v119
	v_cvt_pk_fp8_f32 v122, v124, v125 op_sel:[0,0,1]
	global_store_dwordx2 v[152:153], v[122:123], off offset:1024 nt
	ds_read_b128 v[122:125], v191 offset:2048
	s_waitcnt lgkmcnt(0)
	v_mfma_f32_16x16x32_bf16 v[114:117], v[118:121], v[122:125], v[114:117]
	ds_read_b128 v[118:121], v194
	v_mov_b32_e32 v123, v1
	s_waitcnt lgkmcnt(0)
	v_lshlrev_b32_e32 v125, 16, v120
	v_and_b32_e32 v126, 0xffff0000, v120
	v_cvt_pk_fp8_f32 v123, v125, v126
	v_lshlrev_b32_e32 v122, 16, v121
	v_and_b32_e32 v124, 0xffff0000, v121
	v_lshlrev_b32_e32 v126, 16, v118
	v_cvt_pk_fp8_f32 v123, v122, v124 op_sel:[0,0,1]
	v_and_b32_e32 v127, 0xffff0000, v118
	v_mov_b32_e32 v122, v1
	v_cvt_pk_fp8_f32 v122, v126, v127
	v_lshlrev_b32_e32 v124, 16, v119
	v_and_b32_e32 v125, 0xffff0000, v119
	v_cvt_pk_fp8_f32 v122, v124, v125 op_sel:[0,0,1]
	global_store_dwordx2 v[152:153], v[122:123], off offset:1536 nt
	ds_read_b128 v[122:125], v191 offset:3072
	s_waitcnt lgkmcnt(0)
	v_mfma_f32_16x16x32_bf16 v[114:117], v[118:121], v[122:125], v[114:117]
	ds_read_b128 v[118:121], v195
	v_mov_b32_e32 v123, v1
	s_waitcnt lgkmcnt(0)
	v_lshlrev_b32_e32 v125, 16, v120
	v_and_b32_e32 v126, 0xffff0000, v120
	v_cvt_pk_fp8_f32 v123, v125, v126
	v_lshlrev_b32_e32 v122, 16, v121
	v_and_b32_e32 v124, 0xffff0000, v121
	v_lshlrev_b32_e32 v126, 16, v118
	v_cvt_pk_fp8_f32 v123, v122, v124 op_sel:[0,0,1]
	v_and_b32_e32 v127, 0xffff0000, v118
	v_mov_b32_e32 v122, v1
	v_cvt_pk_fp8_f32 v122, v126, v127
	v_lshlrev_b32_e32 v124, 16, v119
	v_and_b32_e32 v125, 0xffff0000, v119
	v_cvt_pk_fp8_f32 v122, v124, v125 op_sel:[0,0,1]
	global_store_dwordx2 v[152:153], v[122:123], off offset:2048 nt
	ds_read_b128 v[122:125], v191 offset:4096
	s_waitcnt lgkmcnt(0)
	v_mfma_f32_16x16x32_bf16 v[114:117], v[118:121], v[122:125], v[114:117]
	ds_read_b128 v[118:121], v196
	v_mov_b32_e32 v123, v1
	s_waitcnt lgkmcnt(0)
	v_lshlrev_b32_e32 v125, 16, v120
	v_and_b32_e32 v126, 0xffff0000, v120
	v_cvt_pk_fp8_f32 v123, v125, v126
	v_lshlrev_b32_e32 v122, 16, v121
	v_and_b32_e32 v124, 0xffff0000, v121
	v_lshlrev_b32_e32 v126, 16, v118
	v_cvt_pk_fp8_f32 v123, v122, v124 op_sel:[0,0,1]
	v_and_b32_e32 v127, 0xffff0000, v118
	v_mov_b32_e32 v122, v1
	v_cvt_pk_fp8_f32 v122, v126, v127
	v_lshlrev_b32_e32 v124, 16, v119
	v_and_b32_e32 v125, 0xffff0000, v119
	v_cvt_pk_fp8_f32 v122, v124, v125 op_sel:[0,0,1]
	global_store_dwordx2 v[152:153], v[122:123], off offset:2560 nt
	ds_read_b128 v[122:125], v191 offset:5120
	s_waitcnt lgkmcnt(0)
	v_mfma_f32_16x16x32_bf16 v[114:117], v[118:121], v[122:125], v[114:117]
	ds_read_b128 v[118:121], v197
	v_mov_b32_e32 v123, v1
	s_waitcnt lgkmcnt(0)
	v_lshlrev_b32_e32 v125, 16, v120
	v_and_b32_e32 v126, 0xffff0000, v120
	v_cvt_pk_fp8_f32 v123, v125, v126
	v_lshlrev_b32_e32 v122, 16, v121
	v_and_b32_e32 v124, 0xffff0000, v121
	v_lshlrev_b32_e32 v126, 16, v118
	v_cvt_pk_fp8_f32 v123, v122, v124 op_sel:[0,0,1]
	v_and_b32_e32 v127, 0xffff0000, v118
	v_mov_b32_e32 v122, v1
	v_cvt_pk_fp8_f32 v122, v126, v127
	v_lshlrev_b32_e32 v124, 16, v119
	v_and_b32_e32 v125, 0xffff0000, v119
	v_cvt_pk_fp8_f32 v122, v124, v125 op_sel:[0,0,1]
	global_store_dwordx2 v[152:153], v[122:123], off offset:3072 nt
	ds_read_b128 v[122:125], v191 offset:6144
	s_waitcnt lgkmcnt(0)
	v_mfma_f32_16x16x32_bf16 v[114:117], v[118:121], v[122:125], v[114:117]
	ds_read_b128 v[118:121], v198
	v_mov_b32_e32 v123, v1
	s_waitcnt lgkmcnt(0)
	v_lshlrev_b32_e32 v125, 16, v120
	v_and_b32_e32 v126, 0xffff0000, v120
	v_cvt_pk_fp8_f32 v123, v125, v126
	v_lshlrev_b32_e32 v122, 16, v121
	v_and_b32_e32 v124, 0xffff0000, v121
	v_lshlrev_b32_e32 v126, 16, v118
	v_cvt_pk_fp8_f32 v123, v122, v124 op_sel:[0,0,1]
	v_and_b32_e32 v127, 0xffff0000, v118
	v_mov_b32_e32 v122, v1
	v_cvt_pk_fp8_f32 v122, v126, v127
	v_lshlrev_b32_e32 v124, 16, v119
	v_and_b32_e32 v125, 0xffff0000, v119
	v_cvt_pk_fp8_f32 v122, v124, v125 op_sel:[0,0,1]
	global_store_dwordx2 v[152:153], v[122:123], off offset:3584 nt
	ds_read_b128 v[122:125], v191 offset:7168
	s_waitcnt lgkmcnt(0)
	v_mfma_f32_16x16x32_bf16 v[114:117], v[118:121], v[122:125], v[114:117]
	v_mov_b32_e32 v122, v1
	s_waitcnt vmcnt(18)
	v_cvt_pk_fp8_f32 v122, v106, v107
	v_cvt_pk_bf16_f32 v118, v106, v107
	v_cvt_pk_bf16_f32 v119, v108, v109
	v_cvt_pk_bf16_f32 v120, v110, v111
	v_cvt_pk_bf16_f32 v121, v112, v113
	v_cvt_pk_fp8_f32 v122, v108, v109 op_sel:[0,0,1]
	ds_read_b128 v[106:109], v191 offset:8192
	v_mov_b32_e32 v123, v1
	v_cvt_pk_fp8_f32 v123, v110, v111
	s_waitcnt lgkmcnt(0)
	v_mfma_f32_16x16x32_bf16 v[106:109], v[118:121], v[106:109], v[114:117]
	v_cvt_pk_fp8_f32 v123, v112, v113 op_sel:[0,0,1]
	s_nop 1
	v_mov_b32_e32 v114, v1
	s_waitcnt vmcnt(16)
	v_cvt_pk_fp8_f32 v114, v98, v99
	v_add_co_u32_e32 v156, vcc, s96, v152
	v_mov_b32_e32 v115, v1
	s_nop 0
	v_addc_co_u32_e32 v157, vcc, 0, v153, vcc
	global_store_dwordx2 v[156:157], v[122:123], off nt
	v_cvt_pk_bf16_f32 v110, v98, v99
	v_cvt_pk_bf16_f32 v111, v100, v101
	v_cvt_pk_bf16_f32 v112, v102, v103
	v_cvt_pk_bf16_f32 v113, v104, v105
	v_cvt_pk_fp8_f32 v114, v100, v101 op_sel:[0,0,1]
	ds_read_b128 v[98:101], v191 offset:9216
	v_cvt_pk_fp8_f32 v115, v102, v103
	s_waitcnt lgkmcnt(0)
	v_mfma_f32_16x16x32_bf16 v[98:101], v[110:113], v[98:101], v[106:109]
	v_cvt_pk_fp8_f32 v115, v104, v105 op_sel:[0,0,1]
	global_store_dwordx2 v[156:157], v[114:115], off offset:512 nt
	s_and_b64 vcc, exec, s[8:9]
	s_mov_b64 s[36:37], s[18:19]
	s_cbranch_vccnz .LBB0_2306
	s_cmp_lt_i32 s1, 2
	s_cbranch_scc1 .LBB0_2302
	s_cmp_eq_u32 s1, 2
	s_mov_b64 s[4:5], -1
	s_cbranch_scc0 .LBB0_2301
	s_mov_b64 s[4:5], 0

.LBB0_2306:
	s_or_b32 s2, s2, 16
	s_lshl_b32 s4, s2, 10
	s_add_u32 s4, s36, s4
	s_addc_u32 s5, s37, 0
	v_lshl_add_u64 v[102:103], s[4:5], 0, v[0:1]
	v_add_co_u32_e32 v106, vcc, 0x2000, v102
	v_lshl_add_u64 v[104:105], v[102:103], 0, s[64:65]
	s_nop 0
	v_addc_co_u32_e32 v107, vcc, 0, v103, vcc
	v_add_co_u32_e32 v102, vcc, 0x3000, v102
	global_load_dwordx4 v[142:145], v[104:105], off offset:1024 nt
	global_load_dwordx4 v[138:141], v[104:105], off offset:2048 nt
	global_load_dwordx4 v[146:149], v[106:107], off nt
	global_load_dwordx4 v[134:137], v[104:105], off offset:3072 nt
	v_addc_co_u32_e32 v103, vcc, 0, v103, vcc
	global_load_dwordx4 v[130:133], v[102:103], off nt
	global_load_dwordx4 v[126:129], v[102:103], off offset:1024 nt
	global_load_dwordx4 v[122:125], v[102:103], off offset:2048 nt
	global_load_dwordx4 v[118:121], v[102:103], off offset:3072 nt
	s_and_b64 vcc, exec, s[8:9]
	s_mov_b64 s[8:9], s[20:21]
	s_cbranch_vccnz .LBB0_2315
	s_cmp_lt_i32 s1, 2
	s_cbranch_scc1 .LBB0_2311
	s_cmp_eq_u32 s1, 2
	s_mov_b64 s[4:5], -1
	s_cbranch_scc0 .LBB0_2310
	s_mov_b64 s[4:5], 0

.LBB0_2315:
	v_or_b32_e32 v102, s2, v155
	v_lshlrev_b32_e32 v102, 8, v102
	v_mov_b32_e32 v103, v1
	v_lshl_add_u64 v[102:103], s[8:9], 0, v[102:103]
	v_lshl_add_u64 v[102:103], v[150:151], 2, v[102:103]
	global_load_dwordx4 v[114:117], v[102:103], off offset:16 nt
	global_load_dwordx4 v[110:113], v[102:103], off nt
	global_load_dwordx4 v[106:109], v[102:103], off offset:144 nt
	s_nop 0
	global_load_dwordx4 v[102:105], v[102:103], off offset:128 nt
	s_waitcnt vmcnt(27)
	v_cvt_pk_bf16_f32 v200, v22, v23
	v_cvt_pk_bf16_f32 v201, v24, v25
	ds_write_b64 v182, v[200:201] offset:8192
	v_cvt_pk_bf16_f32 v200, v14, v15
	v_cvt_pk_bf16_f32 v201, v16, v17
	ds_write_b64 v183, v[200:201] offset:8704
	v_cvt_pk_bf16_f32 v200, v6, v7
	v_cvt_pk_bf16_f32 v201, v8, v9
	ds_write_b64 v184, v[200:201] offset:9216
	s_waitcnt vmcnt(26)
	v_cvt_pk_bf16_f32 v200, v2, v3
	v_cvt_pk_bf16_f32 v201, v4, v5
	ds_write_b64 v185, v[200:201] offset:9728
	s_waitcnt vmcnt(25)
	v_cvt_pk_bf16_f32 v200, v30, v31
	v_cvt_pk_bf16_f32 v201, v32, v33
	ds_write_b64 v186, v[200:201] offset:10240
	s_waitcnt vmcnt(24)
	v_cvt_pk_bf16_f32 v200, v26, v27
	v_cvt_pk_bf16_f32 v201, v28, v29
	ds_write_b64 v187, v[200:201] offset:10752
	s_waitcnt vmcnt(23)
	v_cvt_pk_bf16_f32 v200, v18, v19
	v_cvt_pk_bf16_f32 v201, v20, v21
	ds_write_b64 v188, v[200:201] offset:11264
	s_waitcnt vmcnt(22)
	v_cvt_pk_bf16_f32 v200, v10, v11
	v_cvt_pk_bf16_f32 v201, v12, v13
	ds_write_b64 v189, v[200:201] offset:11776
	s_cmp_gt_u32 s39, 59
	s_cbranch_scc1 .LBB0_2323
	s_cmp_lt_u32 s39, 12
	s_mov_b64 s[4:5], s[18:19]
	s_cbranch_scc1 .LBB0_2322
	s_lshr_b32 s1, s15, 4
	s_cmp_lt_i32 s1, 2
	s_mov_b64 s[4:5], s[22:23]
	s_cbranch_scc1 .LBB0_2322
	s_cmp_lg_u32 s1, 2
	s_mov_b64 s[4:5], -1
	s_cbranch_scc0 .LBB0_2320
	s_mov_b64 s[4:5], 0

.LBB0_2322:
	s_and_b32 s1, s38, 0x6000
	s_lshl_b32 s1, s1, 2
	s_add_u32 s4, s4, s1
	s_addc_u32 s5, s5, 0
	v_lshl_add_u64 v[10:11], s[4:5], 0, v[0:1]
	v_add_co_u32_e32 v10, vcc, 0x1000, v10
	global_load_dwordx4 v[22:25], v0, s[4:5] nt
	global_load_dwordx4 v[14:17], v0, s[4:5] offset:1024 nt
	global_load_dwordx4 v[6:9], v0, s[4:5] offset:2048 nt
	global_load_dwordx4 v[2:5], v0, s[4:5] offset:3072 nt
	v_addc_co_u32_e32 v11, vcc, 0, v11, vcc
	global_load_dwordx4 v[30:33], v[10:11], off nt
	global_load_dwordx4 v[26:29], v[10:11], off offset:1024 nt
	global_load_dwordx4 v[18:21], v[10:11], off offset:2048 nt
	s_nop 0
	global_load_dwordx4 v[10:13], v[10:11], off offset:3072 nt
.LBB0_2323:
	s_waitcnt vmcnt(9)
	v_cvt_pk_bf16_f32 v146, v146, v147
	v_cvt_pk_bf16_f32 v147, v148, v149
	ds_write_b64 v182, v[146:147] offset:12288
	v_cvt_pk_bf16_f32 v142, v142, v143
	v_cvt_pk_bf16_f32 v143, v144, v145
	ds_write_b64 v183, v[142:143] offset:12800
	v_cvt_pk_bf16_f32 v138, v138, v139
	v_cvt_pk_bf16_f32 v139, v140, v141
	ds_write_b64 v184, v[138:139] offset:13312
	s_waitcnt vmcnt(8)
	v_cvt_pk_bf16_f32 v134, v134, v135
	v_cvt_pk_bf16_f32 v135, v136, v137
	ds_write_b64 v185, v[134:135] offset:13824
	s_waitcnt vmcnt(7)
	v_cvt_pk_bf16_f32 v130, v130, v131
	v_cvt_pk_bf16_f32 v131, v132, v133
	ds_write_b64 v186, v[130:131] offset:14336
	s_waitcnt vmcnt(6)
	v_cvt_pk_bf16_f32 v126, v126, v127
	v_cvt_pk_bf16_f32 v127, v128, v129
	ds_write_b64 v187, v[126:127] offset:14848
	s_waitcnt vmcnt(5)
	v_cvt_pk_bf16_f32 v122, v122, v123
	v_cvt_pk_bf16_f32 v123, v124, v125
	ds_write_b64 v188, v[122:123] offset:15360
	s_waitcnt vmcnt(4)
	v_cvt_pk_bf16_f32 v118, v118, v119
	v_cvt_pk_bf16_f32 v119, v120, v121
	ds_write_b64 v189, v[118:119] offset:15872
	ds_read_b128 v[118:121], v190 offset:8192
	v_mov_b32_e32 v123, v1
	s_waitcnt lgkmcnt(0)
	v_lshlrev_b32_e32 v125, 16, v120
	v_and_b32_e32 v126, 0xffff0000, v120
	v_cvt_pk_fp8_f32 v123, v125, v126
	v_lshlrev_b32_e32 v122, 16, v121
	v_and_b32_e32 v124, 0xffff0000, v121
	v_lshlrev_b32_e32 v126, 16, v118
	v_cvt_pk_fp8_f32 v123, v122, v124 op_sel:[0,0,1]
	v_and_b32_e32 v127, 0xffff0000, v118
	v_mov_b32_e32 v122, v1
	v_cvt_pk_fp8_f32 v122, v126, v127
	v_lshlrev_b32_e32 v124, 16, v119
	v_and_b32_e32 v125, 0xffff0000, v119
	v_mov_b32_e32 v127, v1
	v_cvt_pk_fp8_f32 v122, v124, v125 op_sel:[0,0,1]
	global_store_dwordx2 v[156:157], v[122:123], off offset:1024 nt
	ds_read_b128 v[122:125], v191
	s_waitcnt lgkmcnt(0)
	v_mfma_f32_16x16x32_bf16 v[118:121], v[118:121], v[122:125], 0
	ds_read_b128 v[122:125], v192 offset:8192
	s_waitcnt lgkmcnt(0)
	v_lshlrev_b32_e32 v129, 16, v124
	v_and_b32_e32 v130, 0xffff0000, v124
	v_cvt_pk_fp8_f32 v127, v129, v130
	v_lshlrev_b32_e32 v126, 16, v125
	v_and_b32_e32 v128, 0xffff0000, v125
	v_lshlrev_b32_e32 v130, 16, v122
	v_cvt_pk_fp8_f32 v127, v126, v128 op_sel:[0,0,1]
	v_and_b32_e32 v131, 0xffff0000, v122
	v_mov_b32_e32 v126, v1
	v_cvt_pk_fp8_f32 v126, v130, v131
	v_lshlrev_b32_e32 v128, 16, v123
	v_and_b32_e32 v129, 0xffff0000, v123
	v_cvt_pk_fp8_f32 v126, v128, v129 op_sel:[0,0,1]
	global_store_dwordx2 v[156:157], v[126:127], off offset:1536 nt
	ds_read_b128 v[126:129], v191 offset:1024
	s_waitcnt lgkmcnt(0)
	v_mfma_f32_16x16x32_bf16 v[118:121], v[122:125], v[126:129], v[118:121]
	ds_read_b128 v[122:125], v193 offset:8192
	v_mov_b32_e32 v127, v1
	s_waitcnt lgkmcnt(0)
	v_lshlrev_b32_e32 v129, 16, v124
	v_and_b32_e32 v130, 0xffff0000, v124
	v_cvt_pk_fp8_f32 v127, v129, v130
	v_lshlrev_b32_e32 v126, 16, v125
	v_and_b32_e32 v128, 0xffff0000, v125
	v_lshlrev_b32_e32 v130, 16, v122
	v_cvt_pk_fp8_f32 v127, v126, v128 op_sel:[0,0,1]
	v_and_b32_e32 v131, 0xffff0000, v122
	v_mov_b32_e32 v126, v1
	v_cvt_pk_fp8_f32 v126, v130, v131
	v_lshlrev_b32_e32 v128, 16, v123
	v_and_b32_e32 v129, 0xffff0000, v123
	v_cvt_pk_fp8_f32 v126, v128, v129 op_sel:[0,0,1]
	global_store_dwordx2 v[156:157], v[126:127], off offset:2048 nt
	ds_read_b128 v[126:129], v191 offset:2048
	s_waitcnt lgkmcnt(0)
	v_mfma_f32_16x16x32_bf16 v[118:121], v[122:125], v[126:129], v[118:121]
	ds_read_b128 v[122:125], v194 offset:8192
	v_mov_b32_e32 v127, v1
	s_waitcnt lgkmcnt(0)
	v_lshlrev_b32_e32 v129, 16, v124
	v_and_b32_e32 v130, 0xffff0000, v124
	v_cvt_pk_fp8_f32 v127, v129, v130
	v_lshlrev_b32_e32 v126, 16, v125
	v_and_b32_e32 v128, 0xffff0000, v125
	v_lshlrev_b32_e32 v130, 16, v122
	v_cvt_pk_fp8_f32 v127, v126, v128 op_sel:[0,0,1]
	v_and_b32_e32 v131, 0xffff0000, v122
	v_mov_b32_e32 v126, v1
	v_cvt_pk_fp8_f32 v126, v130, v131
	v_lshlrev_b32_e32 v128, 16, v123
	v_and_b32_e32 v129, 0xffff0000, v123
	v_cvt_pk_fp8_f32 v126, v128, v129 op_sel:[0,0,1]
	global_store_dwordx2 v[156:157], v[126:127], off offset:2560 nt
	ds_read_b128 v[126:129], v191 offset:3072
	s_waitcnt lgkmcnt(0)
	v_mfma_f32_16x16x32_bf16 v[118:121], v[122:125], v[126:129], v[118:121]
	ds_read_b128 v[122:125], v195 offset:8192
	v_mov_b32_e32 v127, v1
	s_waitcnt lgkmcnt(0)
	v_lshlrev_b32_e32 v129, 16, v124
	v_and_b32_e32 v130, 0xffff0000, v124
	v_cvt_pk_fp8_f32 v127, v129, v130
	v_lshlrev_b32_e32 v126, 16, v125
	v_and_b32_e32 v128, 0xffff0000, v125
	v_lshlrev_b32_e32 v130, 16, v122
	v_cvt_pk_fp8_f32 v127, v126, v128 op_sel:[0,0,1]
	v_and_b32_e32 v131, 0xffff0000, v122
	v_mov_b32_e32 v126, v1
	v_cvt_pk_fp8_f32 v126, v130, v131
	v_lshlrev_b32_e32 v128, 16, v123
	v_and_b32_e32 v129, 0xffff0000, v123
	v_cvt_pk_fp8_f32 v126, v128, v129 op_sel:[0,0,1]
	global_store_dwordx2 v[156:157], v[126:127], off offset:3072 nt
	ds_read_b128 v[126:129], v191 offset:4096
	s_waitcnt lgkmcnt(0)
	v_mfma_f32_16x16x32_bf16 v[118:121], v[122:125], v[126:129], v[118:121]
	ds_read_b128 v[122:125], v196 offset:8192
	v_mov_b32_e32 v127, v1
	s_waitcnt lgkmcnt(0)
	v_lshlrev_b32_e32 v129, 16, v124
	v_and_b32_e32 v130, 0xffff0000, v124
	v_cvt_pk_fp8_f32 v127, v129, v130
	v_lshlrev_b32_e32 v126, 16, v125
	v_and_b32_e32 v128, 0xffff0000, v125
	v_lshlrev_b32_e32 v130, 16, v122
	v_cvt_pk_fp8_f32 v127, v126, v128 op_sel:[0,0,1]
	v_and_b32_e32 v131, 0xffff0000, v122
	v_mov_b32_e32 v126, v1
	v_cvt_pk_fp8_f32 v126, v130, v131
	v_lshlrev_b32_e32 v128, 16, v123
	v_and_b32_e32 v129, 0xffff0000, v123
	v_cvt_pk_fp8_f32 v126, v128, v129 op_sel:[0,0,1]
	global_store_dwordx2 v[156:157], v[126:127], off offset:3584 nt
	ds_read_b128 v[126:129], v191 offset:5120
	s_waitcnt lgkmcnt(0)
	v_mfma_f32_16x16x32_bf16 v[120:123], v[122:125], v[126:129], v[118:121]
	ds_read_b128 v[124:127], v197 offset:8192
	v_mov_b32_e32 v129, v1
	s_movk_i32 s1, 0x2000
	s_waitcnt lgkmcnt(0)
	v_lshlrev_b32_e32 v128, 16, v126
	v_and_b32_e32 v130, 0xffff0000, v126
	v_cvt_pk_fp8_f32 v129, v128, v130
	v_lshlrev_b32_e32 v130, 16, v124
	v_and_b32_e32 v131, 0xffff0000, v124
	v_mov_b32_e32 v128, v1
	v_cvt_pk_fp8_f32 v128, v130, v131
	v_lshlrev_b32_e32 v118, 16, v127
	v_and_b32_e32 v119, 0xffff0000, v127
	v_cvt_pk_fp8_f32 v129, v118, v119 op_sel:[0,0,1]
	v_lshlrev_b32_e32 v118, 16, v125
	v_and_b32_e32 v119, 0xffff0000, v125
	v_cvt_pk_fp8_f32 v128, v118, v119 op_sel:[0,0,1]
	v_add_co_u32_e32 v118, vcc, s1, v152
	s_nop 1
	v_addc_co_u32_e32 v119, vcc, 0, v153, vcc
	global_store_dwordx2 v[118:119], v[128:129], off nt
	ds_read_b128 v[128:131], v191 offset:6144
	s_waitcnt lgkmcnt(0)
	v_mfma_f32_16x16x32_bf16 v[120:123], v[124:127], v[128:131], v[120:123]
	ds_read_b128 v[124:127], v198 offset:8192
	v_mov_b32_e32 v129, v1
	s_waitcnt lgkmcnt(0)
	v_lshlrev_b32_e32 v131, 16, v126
	v_and_b32_e32 v132, 0xffff0000, v126
	v_cvt_pk_fp8_f32 v129, v131, v132
	v_lshlrev_b32_e32 v128, 16, v127
	v_and_b32_e32 v130, 0xffff0000, v127
	v_lshlrev_b32_e32 v132, 16, v124
	v_cvt_pk_fp8_f32 v129, v128, v130 op_sel:[0,0,1]
	v_and_b32_e32 v133, 0xffff0000, v124
	v_mov_b32_e32 v128, v1
	v_cvt_pk_fp8_f32 v128, v132, v133
	v_lshlrev_b32_e32 v130, 16, v125
	v_and_b32_e32 v131, 0xffff0000, v125
	v_cvt_pk_fp8_f32 v128, v130, v131 op_sel:[0,0,1]
	global_store_dwordx2 v[118:119], v[128:129], off offset:512 nt
	ds_read_b128 v[128:131], v191 offset:7168
	s_waitcnt lgkmcnt(0)
	v_mfma_f32_16x16x32_bf16 v[120:123], v[124:127], v[128:131], v[120:123]
	v_mov_b32_e32 v128, v1
	s_waitcnt vmcnt(10)
	v_cvt_pk_fp8_f32 v128, v110, v111
	v_cvt_pk_bf16_f32 v124, v110, v111
	v_cvt_pk_bf16_f32 v125, v112, v113
	v_cvt_pk_bf16_f32 v126, v114, v115
	v_cvt_pk_bf16_f32 v127, v116, v117
	v_cvt_pk_fp8_f32 v128, v112, v113 op_sel:[0,0,1]
	ds_read_b128 v[110:113], v191 offset:8192
	v_mov_b32_e32 v129, v1
	v_cvt_pk_fp8_f32 v129, v114, v115
	s_waitcnt lgkmcnt(0)
	v_mfma_f32_16x16x32_bf16 v[110:113], v[124:127], v[110:113], v[120:123]
	v_cvt_pk_fp8_f32 v129, v116, v117 op_sel:[0,0,1]
	s_nop 1
	v_mov_b32_e32 v120, v1
	s_waitcnt vmcnt(8)
	v_cvt_pk_fp8_f32 v120, v102, v103
	v_mov_b32_e32 v121, v1
	global_store_dwordx2 v[118:119], v[128:129], off offset:1024 nt
	v_cvt_pk_bf16_f32 v114, v102, v103
	v_cvt_pk_bf16_f32 v115, v104, v105
	v_cvt_pk_bf16_f32 v116, v106, v107
	v_cvt_pk_bf16_f32 v117, v108, v109
	v_cvt_pk_fp8_f32 v120, v104, v105 op_sel:[0,0,1]
	ds_read_b128 v[102:105], v191 offset:9216
	v_cvt_pk_fp8_f32 v121, v106, v107
	s_waitcnt lgkmcnt(0)
	v_mfma_f32_16x16x32_bf16 v[102:105], v[114:117], v[102:105], v[110:113]
	v_cvt_pk_fp8_f32 v121, v108, v109 op_sel:[0,0,1]
	global_store_dwordx2 v[118:119], v[120:121], off offset:1536 nt
	v_max_f32_e32 v106, v99, v99
	v_max_f32_e32 v107, v98, v98
	v_max_f32_e32 v106, v107, v106
	v_max_f32_e32 v107, v101, v101
	v_max_f32_e32 v108, v100, v100
	v_max_f32_e32 v107, v108, v107
	v_max_f32_e32 v108, v105, v105
	v_max_f32_e32 v109, v104, v104
	v_max_f32_e32 v108, v109, v108
	v_max3_f32 v108, v102, v103, v108
	v_max3_f32 v106, v106, v107, v108
	ds_bpermute_b32 v107, v163, v106
	s_waitcnt lgkmcnt(0)
	v_max_f32_e32 v107, v107, v107
	v_max_f32_e32 v106, v106, v107
	ds_bpermute_b32 v107, v164, v106
	s_waitcnt lgkmcnt(0)
	v_max_f32_e32 v107, v107, v107
	v_max_f32_e32 v106, v106, v107
	v_add_f32_e32 v107, 0x41000000, v154
	v_cmp_gt_f32_e32 vcc, v106, v107
	s_cbranch_vccz .LBB0_2269
	v_max_f32_e32 v106, v106, v106
	v_max_f32_e32 v107, v154, v154
	v_max_f32_e32 v107, v107, v106
	v_sub_f32_e32 v106, v154, v107
	v_exp_f32_e32 v106, v106
	v_mov_b32_e32 v154, v107
	v_pk_mul_f32 v[36:37], v[36:37], v[106:107] op_sel_hi:[1,0]
	v_pk_mul_f32 v[34:35], v[34:35], v[106:107] op_sel_hi:[1,0]
	v_pk_mul_f32 v[96:97], v[96:97], v[106:107] op_sel_hi:[1,0]
	v_pk_mul_f32 v[94:95], v[94:95], v[106:107] op_sel_hi:[1,0]
	v_pk_mul_f32 v[92:93], v[92:93], v[106:107] op_sel_hi:[1,0]
	v_pk_mul_f32 v[90:91], v[90:91], v[106:107] op_sel_hi:[1,0]
	v_pk_mul_f32 v[88:89], v[88:89], v[106:107] op_sel_hi:[1,0]
	v_pk_mul_f32 v[86:87], v[86:87], v[106:107] op_sel_hi:[1,0]
	v_pk_mul_f32 v[84:85], v[84:85], v[106:107] op_sel_hi:[1,0]
	v_pk_mul_f32 v[82:83], v[82:83], v[106:107] op_sel_hi:[1,0]
	v_pk_mul_f32 v[80:81], v[80:81], v[106:107] op_sel_hi:[1,0]
	v_pk_mul_f32 v[78:79], v[78:79], v[106:107] op_sel_hi:[1,0]
	v_pk_mul_f32 v[76:77], v[76:77], v[106:107] op_sel_hi:[1,0]
	v_pk_mul_f32 v[74:75], v[74:75], v[106:107] op_sel_hi:[1,0]
	v_pk_mul_f32 v[72:73], v[72:73], v[106:107] op_sel_hi:[1,0]
	v_pk_mul_f32 v[70:71], v[70:71], v[106:107] op_sel_hi:[1,0]
	v_pk_mul_f32 v[68:69], v[68:69], v[106:107] op_sel_hi:[1,0]
	v_pk_mul_f32 v[66:67], v[66:67], v[106:107] op_sel_hi:[1,0]
	v_pk_mul_f32 v[64:65], v[64:65], v[106:107] op_sel_hi:[1,0]
	v_pk_mul_f32 v[62:63], v[62:63], v[106:107] op_sel_hi:[1,0]
	v_pk_mul_f32 v[60:61], v[60:61], v[106:107] op_sel_hi:[1,0]
	v_pk_mul_f32 v[58:59], v[58:59], v[106:107] op_sel_hi:[1,0]
	v_pk_mul_f32 v[56:57], v[56:57], v[106:107] op_sel_hi:[1,0]
	v_pk_mul_f32 v[54:55], v[54:55], v[106:107] op_sel_hi:[1,0]
	v_pk_mul_f32 v[52:53], v[52:53], v[106:107] op_sel_hi:[1,0]
	v_pk_mul_f32 v[50:51], v[50:51], v[106:107] op_sel_hi:[1,0]
	v_pk_mul_f32 v[48:49], v[48:49], v[106:107] op_sel_hi:[1,0]
	v_pk_mul_f32 v[46:47], v[46:47], v[106:107] op_sel_hi:[1,0]
	v_pk_mul_f32 v[44:45], v[44:45], v[106:107] op_sel_hi:[1,0]
	v_pk_mul_f32 v[42:43], v[42:43], v[106:107] op_sel_hi:[1,0]
	v_pk_mul_f32 v[40:41], v[40:41], v[106:107] op_sel_hi:[1,0]
	v_pk_mul_f32 v[38:39], v[38:39], v[106:107] op_sel_hi:[1,0]
	v_mul_f32_e32 v165, v165, v106
	s_branch .LBB0_2269
